# attention kt loops: first-body fragment addresses computed before the barrier and its LDS reads issued right after it, ahead of the next-tile LDS-DMA issue
# baseline (speedup 1.0000x reference)
; #define MFMA32(a, b, c) __builtin_amdgcn_mfma_f32_32x32x16_bf16((a), (b), (c), 0, 0, 0)
; DI float fadd1(float a, float b) { float r; asm("v_add_f32 %0, %1, %2" : "=v"(r) : "v"(a), "v"(b)); return r; }
; template <int NKS>
; DI void attn_tile(const Params& p, int layer, int seq, int slot, int qt, char* smem, bool wr = true) {
;     ...
;     for (int kt = 0; kt < nkt; ++kt) {
;       asm volatile("s_waitcnt vmcnt(0)" ::: "memory");
;       __syncthreads();
;       if (kt + 1 < nkt) stage(kt + 1);
; #pragma unroll 1
;       for (int kh = 0; kh < 2; ++kh) {
;       const u16* sK = (const u16*)(smem + (kt & 1) * 32768 + kh * 8192);
;       const u16* sV = (const u16*)(smem + (kt & 1) * 32768 + 16384 + kh * 8192);
;       auto kb_body = [&](int kb) {
;         bf16x8 kf[NKS];
; #pragma unroll
;         for (int ks = 0; ks < NKS; ++ks) kf[ks] = *(const bf16x8*)(sK + swz(32 * kb + r, 2 * (ks0 + ks) + h));
;         bf16x8 pk[2][2];
; #pragma unroll
;         for (int qb = 0; qb < 2; ++qb) {
;           f32x16 st;
; #pragma unroll
;           for (int i = 0; i < 16; ++i) st[i] = SUB ? ncb[qb] : 0.f;
; #pragma unroll
;           for (int ks = 0; ks < NKS; ++ks) st = MFMA32(kf[ks], qf[qb][ks], st);
;           if constexpr (SUB) {
;             float ls = 0.f;
; #pragma unroll
;             for (int i = 0; i < 16; ++i) { float e = __builtin_amdgcn_exp2f(st[i]); st[i] = e; ls = fadd1(ls, e); }
;             lsum[qb] += ls;
;             pk[qb][0] = pack8(st, 0); pk[qb][1] = pack8(st, 1);
;           } else {
; #pragma unroll
;             for (int i = 0; i < 16; ++i) st[i] = __builtin_amdgcn_exp2f(st[i]);
;             pk[qb][0] = pack8(st, 0); pk[qb][1] = pack8(st, 1);
;             ls4[qb] = __builtin_amdgcn_mfma_f32_16x16x32_bf16(selA, pk[qb][0], ls4[qb], 0, 0, 0);
;             ls4[qb] = __builtin_amdgcn_mfma_f32_16x16x32_bf16(selA, pk[qb][1], ls4[qb], 0, 0, 0);
;           }
;         }
; #pragma unroll
;         for (int eb = 0; eb < 2; ++eb)
; #pragma unroll
;           for (int s2 = 0; s2 < 2; ++s2) {
;             bf16x8 vf = *(const bf16x8*)(sV + swz(32 * eb + r, 4 * kb + 2 * s2 + h));
; #pragma unroll
;             for (int qb = 0; qb < 2; ++qb) O[qb][eb] = MFMA32(vf, pk[qb][s2], O[qb][eb]);
;           }
;       };
.LBB0_637:
	s_waitcnt vmcnt(0)
	s_lshl_b32 s4, s29, 15
	s_and_b32 s4, s4, 0x8000
	v_lshl_add_u32 v128, v187, 1, s4
	v_lshl_add_u32 v130, v188, 1, s4
	v_lshl_add_u32 v131, v189, 1, s4
	v_lshl_add_u32 v191, v190, 1, s4
	s_add_i32 s28, s29, 1
	s_cmp_ge_u32 s28, s25
	s_waitcnt vmcnt(0)
	s_barrier
	ds_read_b128 v[192:195], v128
	ds_read_b128 v[196:199], v130
	ds_read_b128 v[200:203], v131
	ds_read_b128 v[204:207], v191
	ds_read_b128 v[208:211], v128 offset:4096
	ds_read_b128 v[212:215], v130 offset:4096
	ds_read_b128 v[216:219], v131 offset:4096
	ds_read_b128 v[220:223], v191 offset:4096
	ds_read_b128 v[224:227], v128 offset:16384
	ds_read_b128 v[228:231], v128 offset:20480
	s_cbranch_scc1 .LBB0_639
	s_lshl_b32 s4, s28, 15
	s_and_b32 s4, s4, 0x8000
	s_lshl_b32 s14, s28, 8
	s_add_i32 s4, s26, s4
	s_add_i32 s30, s14, s27
	s_add_i32 s5, s4, 0x4000
	s_lshl_b32 s31, s30, 7
	s_mov_b32 m0, s4
	s_mov_b32 s14, s10
	buffer_load_dwordx4 v185, s[8:11], s31 offen lds
	s_mov_b32 s15, s11
	s_mov_b32 m0, s5
	s_or_b32 s5, s31, 0x2000
	buffer_load_dwordx4 v186, s[12:15], s30 offen lds
	s_add_i32 m0, s4, 0x1000
	s_nop 0
	buffer_load_dwordx4 v185, s[8:11], s5 offen lds
	s_add_i32 m0, s4, 0x5000
	s_add_i32 s5, s30, 0x300000
	buffer_load_dwordx4 v186, s[12:15], s5 offen lds
	s_or_b32 s5, s30, 0x80
	s_add_i32 m0, s4, 0x2000
	s_lshl_b32 s34, s5, 7
	buffer_load_dwordx4 v185, s[8:11], s34 offen lds
	s_add_i32 m0, s4, 0x6000
	s_add_i32 s30, s30, 0x300080
	buffer_load_dwordx4 v186, s[12:15], s5 offen lds
	s_add_i32 m0, s4, 0x3000
	s_or_b32 s5, s31, 0x6000
	buffer_load_dwordx4 v185, s[8:11], s5 offen lds
	s_add_i32 m0, s4, 0x7000
	s_nop 0
	buffer_load_dwordx4 v186, s[12:15], s30 offen lds
.LBB0_639:
.LBB0_640:
	s_waitcnt lgkmcnt(8)
	v_mfma_f32_32x32x16_bf16 v[112:127], v[192:195], v[132:135], 0
	v_mfma_f32_32x32x16_bf16 v[112:127], v[196:199], v[136:139], v[112:127]
	s_waitcnt lgkmcnt(6)
	v_mfma_f32_32x32x16_bf16 v[112:127], v[200:203], v[140:143], v[112:127]
	v_mfma_f32_32x32x16_bf16 v[112:127], v[204:207], v[144:147], v[112:127]
	v_mfma_f32_32x32x16_bf16 v[96:111], v[192:195], v[148:151], 0
	v_mfma_f32_32x32x16_bf16 v[96:111], v[196:199], v[152:155], v[96:111]
	v_mfma_f32_32x32x16_bf16 v[96:111], v[200:203], v[156:159], v[96:111]
	v_mfma_f32_32x32x16_bf16 v[96:111], v[204:207], v[160:163], v[96:111]
	ds_read_b128 v[192:195], v130 offset:16384
	ds_read_b128 v[196:199], v130 offset:20480
	ds_read_b128 v[200:203], v131 offset:16384
	ds_read_b128 v[204:207], v131 offset:20480
	s_waitcnt lgkmcnt(9)
	v_mfma_f32_32x32x16_bf16 v[64:79], v[208:211], v[132:135], 0
	s_nop 1
	v_exp_f32_e32 v112, v112
	v_exp_f32_e32 v113, v113
	v_exp_f32_e32 v114, v114
	v_exp_f32_e32 v115, v115
	v_cvt_pk_bf16_f32 v112, v112, v113
	v_cvt_pk_bf16_f32 v113, v114, v115
	s_waitcnt lgkmcnt(6)
	v_mfma_f32_32x32x16_bf16 v[64:79], v[212:215], v[136:139], v[64:79]
	v_exp_f32_e32 v116, v116
	v_exp_f32_e32 v117, v117
	v_exp_f32_e32 v118, v118
	v_exp_f32_e32 v119, v119
	v_cvt_pk_bf16_f32 v114, v116, v117
	v_cvt_pk_bf16_f32 v115, v118, v119
	v_mfma_f32_32x32x16_bf16 v[64:79], v[216:219], v[140:143], v[64:79]
	v_exp_f32_e32 v120, v120
	v_exp_f32_e32 v121, v121
	v_exp_f32_e32 v122, v122
	v_exp_f32_e32 v123, v123
	v_cvt_pk_bf16_f32 v116, v120, v121
	v_cvt_pk_bf16_f32 v117, v122, v123
	v_mfma_f32_32x32x16_bf16 v[64:79], v[220:223], v[144:147], v[64:79]
	s_waitcnt lgkmcnt(4)
	v_mfma_f32_32x32x16_bf16 v[48:63], v[224:227], v[112:115], v[48:63]
	v_exp_f32_e32 v124, v124
	v_exp_f32_e32 v125, v125
	v_exp_f32_e32 v126, v126
	v_exp_f32_e32 v127, v127
	v_cvt_pk_bf16_f32 v118, v124, v125
	v_cvt_pk_bf16_f32 v119, v126, v127
	v_mfma_f32_32x32x16_bf16 v[80:95], v[208:211], v[148:151], 0
	v_mfma_f32_32x32x16_bf16 v[32:47], v[228:231], v[112:115], v[32:47]
	v_exp_f32_e32 v96, v96
	v_exp_f32_e32 v97, v97
	v_exp_f32_e32 v98, v98
	v_exp_f32_e32 v99, v99
	v_cvt_pk_bf16_f32 v96, v96, v97
	v_cvt_pk_bf16_f32 v97, v98, v99
	v_mfma_f32_16x16x32_bf16 v[164:167], v[172:175], v[112:115], v[164:167]
	v_mfma_f32_32x32x16_bf16 v[80:95], v[212:215], v[152:155], v[80:95]
	v_exp_f32_e32 v100, v100
	v_exp_f32_e32 v101, v101
	v_exp_f32_e32 v102, v102
	v_exp_f32_e32 v103, v103
	v_cvt_pk_bf16_f32 v98, v100, v101
	v_cvt_pk_bf16_f32 v99, v102, v103
	v_mfma_f32_32x32x16_bf16 v[80:95], v[216:219], v[156:159], v[80:95]
	s_waitcnt lgkmcnt(2)
	v_mfma_f32_32x32x16_bf16 v[48:63], v[192:195], v[116:119], v[48:63]
	v_exp_f32_e32 v104, v104
	v_exp_f32_e32 v105, v105
	v_exp_f32_e32 v106, v106
	v_exp_f32_e32 v107, v107
	v_cvt_pk_bf16_f32 v100, v104, v105
	v_cvt_pk_bf16_f32 v101, v106, v107
	v_mfma_f32_32x32x16_bf16 v[32:47], v[196:199], v[116:119], v[32:47]
	v_mfma_f32_16x16x32_bf16 v[164:167], v[172:175], v[116:119], v[164:167]
	v_exp_f32_e32 v108, v108
	v_exp_f32_e32 v109, v109
	v_exp_f32_e32 v110, v110
	v_exp_f32_e32 v111, v111
	v_cvt_pk_bf16_f32 v102, v108, v109
	v_cvt_pk_bf16_f32 v103, v110, v111
	v_mfma_f32_32x32x16_bf16 v[80:95], v[220:223], v[160:163], v[80:95]
	ds_read_b128 v[208:211], v191 offset:16384
	ds_read_b128 v[212:215], v191 offset:20480
	v_mfma_f32_32x32x16_bf16 v[16:31], v[224:227], v[96:99], v[16:31]
	v_exp_f32_e32 v64, v64
	v_exp_f32_e32 v65, v65
	v_exp_f32_e32 v66, v66
	v_exp_f32_e32 v67, v67
	v_cvt_pk_bf16_f32 v64, v64, v65
	v_cvt_pk_bf16_f32 v65, v66, v67
	v_mfma_f32_32x32x16_bf16 v[0:15], v[228:231], v[96:99], v[0:15]
	v_mfma_f32_16x16x32_bf16 v[168:171], v[172:175], v[96:99], v[168:171]
	v_exp_f32_e32 v68, v68
	v_exp_f32_e32 v69, v69
	v_exp_f32_e32 v70, v70
	v_exp_f32_e32 v71, v71
	v_cvt_pk_bf16_f32 v66, v68, v69
	v_cvt_pk_bf16_f32 v67, v70, v71
	v_mfma_f32_32x32x16_bf16 v[16:31], v[192:195], v[100:103], v[16:31]
	v_mfma_f32_32x32x16_bf16 v[0:15], v[196:199], v[100:103], v[0:15]
	v_exp_f32_e32 v72, v72
	v_exp_f32_e32 v73, v73
	v_exp_f32_e32 v74, v74
	v_exp_f32_e32 v75, v75
	v_cvt_pk_bf16_f32 v68, v72, v73
	v_cvt_pk_bf16_f32 v69, v74, v75
	v_mfma_f32_16x16x32_bf16 v[168:171], v[172:175], v[100:103], v[168:171]
	s_waitcnt lgkmcnt(2)
; #define MFMA32(a, b, c) __builtin_amdgcn_mfma_f32_32x32x16_bf16((a), (b), (c), 0, 0, 0)
; DI float fadd1(float a, float b) { float r; asm("v_add_f32 %0, %1, %2" : "=v"(r) : "v"(a), "v"(b)); return r; }
; template <int NKS>
; DI void attn_tile(const Params& p, int layer, int seq, int slot, int qt, char* smem, bool wr = true) {
;     ...
;       auto kb_body = [&](int kb) {
;         bf16x8 kf[NKS];
; #pragma unroll
;         for (int ks = 0; ks < NKS; ++ks) kf[ks] = *(const bf16x8*)(sK + swz(32 * kb + r, 2 * (ks0 + ks) + h));
;         bf16x8 pk[2][2];
; #pragma unroll
;         for (int qb = 0; qb < 2; ++qb) {
;           f32x16 st;
; #pragma unroll
;           for (int i = 0; i < 16; ++i) st[i] = SUB ? ncb[qb] : 0.f;
; #pragma unroll
;           for (int ks = 0; ks < NKS; ++ks) st = MFMA32(kf[ks], qf[qb][ks], st);
;           if constexpr (SUB) {
;             float ls = 0.f;
; #pragma unroll
;             for (int i = 0; i < 16; ++i) { float e = __builtin_amdgcn_exp2f(st[i]); st[i] = e; ls = fadd1(ls, e); }
;             lsum[qb] += ls;
;             pk[qb][0] = pack8(st, 0); pk[qb][1] = pack8(st, 1);
;           } else {
; #pragma unroll
;             for (int i = 0; i < 16; ++i) st[i] = __builtin_amdgcn_exp2f(st[i]);
;             pk[qb][0] = pack8(st, 0); pk[qb][1] = pack8(st, 1);
;             ls4[qb] = __builtin_amdgcn_mfma_f32_16x16x32_bf16(selA, pk[qb][0], ls4[qb], 0, 0, 0);
;             ls4[qb] = __builtin_amdgcn_mfma_f32_16x16x32_bf16(selA, pk[qb][1], ls4[qb], 0, 0, 0);
;           }
;         }
; #pragma unroll
;         for (int eb = 0; eb < 2; ++eb)
; #pragma unroll
;           for (int s2 = 0; s2 < 2; ++s2) {
;             bf16x8 vf = *(const bf16x8*)(sV + swz(32 * eb + r, 4 * kb + 2 * s2 + h));
; #pragma unroll
;             for (int qb = 0; qb < 2; ++qb) O[qb][eb] = MFMA32(vf, pk[qb][s2], O[qb][eb]);
;           }
;       };
;       if constexpr (SUB) {
; #pragma unroll 1
;         for (int kb = 0; kb < 2; ++kb) kb_body(kb);
;       } else {
;         kb_body(0); kb_body(1);
	v_mfma_f32_32x32x16_bf16 v[48:63], v[200:203], v[64:67], v[48:63]
	v_exp_f32_e32 v76, v76
	v_exp_f32_e32 v77, v77
	v_exp_f32_e32 v78, v78
	v_exp_f32_e32 v79, v79
	v_cvt_pk_bf16_f32 v70, v76, v77
	v_cvt_pk_bf16_f32 v71, v78, v79
	v_mfma_f32_32x32x16_bf16 v[32:47], v[204:207], v[64:67], v[32:47]
	v_mfma_f32_16x16x32_bf16 v[164:167], v[172:175], v[64:67], v[164:167]
	v_exp_f32_e32 v80, v80
	v_exp_f32_e32 v81, v81
	v_exp_f32_e32 v82, v82
	v_exp_f32_e32 v83, v83
	v_cvt_pk_bf16_f32 v80, v80, v81
	v_cvt_pk_bf16_f32 v81, v82, v83
	s_waitcnt lgkmcnt(0)
	v_mfma_f32_32x32x16_bf16 v[48:63], v[208:211], v[68:71], v[48:63]
	v_exp_f32_e32 v84, v84
	v_exp_f32_e32 v85, v85
	v_exp_f32_e32 v86, v86
	v_exp_f32_e32 v87, v87
	v_cvt_pk_bf16_f32 v82, v84, v85
	v_cvt_pk_bf16_f32 v83, v86, v87
	v_mfma_f32_32x32x16_bf16 v[32:47], v[212:215], v[68:71], v[32:47]
	v_mfma_f32_16x16x32_bf16 v[164:167], v[172:175], v[68:71], v[164:167]
	v_exp_f32_e32 v88, v88
	v_exp_f32_e32 v89, v89
	v_exp_f32_e32 v90, v90
	v_exp_f32_e32 v91, v91
	v_cvt_pk_bf16_f32 v84, v88, v89
	v_cvt_pk_bf16_f32 v85, v90, v91
	v_mfma_f32_32x32x16_bf16 v[16:31], v[200:203], v[80:83], v[16:31]
	v_exp_f32_e32 v92, v92
	v_exp_f32_e32 v93, v93
	v_exp_f32_e32 v94, v94
	v_exp_f32_e32 v95, v95
	v_cvt_pk_bf16_f32 v86, v92, v93
	v_cvt_pk_bf16_f32 v87, v94, v95
	v_mfma_f32_32x32x16_bf16 v[0:15], v[204:207], v[80:83], v[0:15]
	v_mfma_f32_16x16x32_bf16 v[168:171], v[172:175], v[80:83], v[168:171]
	v_mfma_f32_32x32x16_bf16 v[16:31], v[208:211], v[84:87], v[16:31]
	v_mfma_f32_32x32x16_bf16 v[0:15], v[212:215], v[84:87], v[0:15]
	v_mfma_f32_16x16x32_bf16 v[168:171], v[172:175], v[84:87], v[168:171]
	ds_read_b128 v[192:195], v128 offset:8192
	ds_read_b128 v[196:199], v130 offset:8192
	ds_read_b128 v[200:203], v131 offset:8192
	ds_read_b128 v[204:207], v191 offset:8192
	ds_read_b128 v[208:211], v128 offset:12288
	ds_read_b128 v[212:215], v130 offset:12288
	ds_read_b128 v[216:219], v131 offset:12288
	ds_read_b128 v[220:223], v191 offset:12288
	ds_read_b128 v[224:227], v128 offset:24576
	ds_read_b128 v[228:231], v128 offset:28672
	s_waitcnt lgkmcnt(8)
	v_mfma_f32_32x32x16_bf16 v[112:127], v[192:195], v[132:135], 0
	v_mfma_f32_32x32x16_bf16 v[112:127], v[196:199], v[136:139], v[112:127]
	s_waitcnt lgkmcnt(6)
	v_mfma_f32_32x32x16_bf16 v[112:127], v[200:203], v[140:143], v[112:127]
	v_mfma_f32_32x32x16_bf16 v[112:127], v[204:207], v[144:147], v[112:127]
	v_mfma_f32_32x32x16_bf16 v[96:111], v[192:195], v[148:151], 0
	v_mfma_f32_32x32x16_bf16 v[96:111], v[196:199], v[152:155], v[96:111]
	v_mfma_f32_32x32x16_bf16 v[96:111], v[200:203], v[156:159], v[96:111]
	v_mfma_f32_32x32x16_bf16 v[96:111], v[204:207], v[160:163], v[96:111]
	ds_read_b128 v[192:195], v130 offset:24576
	ds_read_b128 v[196:199], v130 offset:28672
	ds_read_b128 v[200:203], v131 offset:24576
	ds_read_b128 v[204:207], v131 offset:28672
	s_waitcnt lgkmcnt(9)
	v_mfma_f32_32x32x16_bf16 v[64:79], v[208:211], v[132:135], 0
	s_nop 1
	v_exp_f32_e32 v112, v112
	v_exp_f32_e32 v113, v113
	v_exp_f32_e32 v114, v114
	v_exp_f32_e32 v115, v115
	v_cvt_pk_bf16_f32 v112, v112, v113
	v_cvt_pk_bf16_f32 v113, v114, v115
	s_waitcnt lgkmcnt(6)
	v_mfma_f32_32x32x16_bf16 v[64:79], v[212:215], v[136:139], v[64:79]
	v_exp_f32_e32 v116, v116
	v_exp_f32_e32 v117, v117
	v_exp_f32_e32 v118, v118
	v_exp_f32_e32 v119, v119
	v_cvt_pk_bf16_f32 v114, v116, v117
	v_cvt_pk_bf16_f32 v115, v118, v119
	v_mfma_f32_32x32x16_bf16 v[64:79], v[216:219], v[140:143], v[64:79]
	v_exp_f32_e32 v120, v120
	v_exp_f32_e32 v121, v121
	v_exp_f32_e32 v122, v122
	v_exp_f32_e32 v123, v123
	v_cvt_pk_bf16_f32 v116, v120, v121
	v_cvt_pk_bf16_f32 v117, v122, v123
	v_mfma_f32_32x32x16_bf16 v[64:79], v[220:223], v[144:147], v[64:79]
	s_waitcnt lgkmcnt(4)
; #define MFMA32(a, b, c) __builtin_amdgcn_mfma_f32_32x32x16_bf16((a), (b), (c), 0, 0, 0)
; DI float fadd1(float a, float b) { float r; asm("v_add_f32 %0, %1, %2" : "=v"(r) : "v"(a), "v"(b)); return r; }
; template <int NKS>
; DI void attn_tile(const Params& p, int layer, int seq, int slot, int qt, char* smem, bool wr = true) {
;     ...
;       auto kb_body = [&](int kb) {
;         bf16x8 kf[NKS];
; #pragma unroll
;         for (int ks = 0; ks < NKS; ++ks) kf[ks] = *(const bf16x8*)(sK + swz(32 * kb + r, 2 * (ks0 + ks) + h));
;         bf16x8 pk[2][2];
; #pragma unroll
;         for (int qb = 0; qb < 2; ++qb) {
;           f32x16 st;
; #pragma unroll
;           for (int i = 0; i < 16; ++i) st[i] = SUB ? ncb[qb] : 0.f;
; #pragma unroll
;           for (int ks = 0; ks < NKS; ++ks) st = MFMA32(kf[ks], qf[qb][ks], st);
;           if constexpr (SUB) {
;             float ls = 0.f;
; #pragma unroll
;             for (int i = 0; i < 16; ++i) { float e = __builtin_amdgcn_exp2f(st[i]); st[i] = e; ls = fadd1(ls, e); }
;             lsum[qb] += ls;
;             pk[qb][0] = pack8(st, 0); pk[qb][1] = pack8(st, 1);
;           } else {
; #pragma unroll
;             for (int i = 0; i < 16; ++i) st[i] = __builtin_amdgcn_exp2f(st[i]);
;             pk[qb][0] = pack8(st, 0); pk[qb][1] = pack8(st, 1);
;             ls4[qb] = __builtin_amdgcn_mfma_f32_16x16x32_bf16(selA, pk[qb][0], ls4[qb], 0, 0, 0);
;             ls4[qb] = __builtin_amdgcn_mfma_f32_16x16x32_bf16(selA, pk[qb][1], ls4[qb], 0, 0, 0);
;           }
;         }
; #pragma unroll
;         for (int eb = 0; eb < 2; ++eb)
; #pragma unroll
;           for (int s2 = 0; s2 < 2; ++s2) {
;             bf16x8 vf = *(const bf16x8*)(sV + swz(32 * eb + r, 4 * kb + 2 * s2 + h));
; #pragma unroll
;             for (int qb = 0; qb < 2; ++qb) O[qb][eb] = MFMA32(vf, pk[qb][s2], O[qb][eb]);
;           }
;       };
;       if constexpr (SUB) {
; #pragma unroll 1
;         for (int kb = 0; kb < 2; ++kb) kb_body(kb);
;       } else {
;         kb_body(0); kb_body(1);
;       }
;       }
;     }
	v_mfma_f32_32x32x16_bf16 v[48:63], v[224:227], v[112:115], v[48:63]
	v_exp_f32_e32 v124, v124
	v_exp_f32_e32 v125, v125
	v_exp_f32_e32 v126, v126
	v_exp_f32_e32 v127, v127
	v_cvt_pk_bf16_f32 v118, v124, v125
	v_cvt_pk_bf16_f32 v119, v126, v127
	v_mfma_f32_32x32x16_bf16 v[80:95], v[208:211], v[148:151], 0
	v_mfma_f32_32x32x16_bf16 v[32:47], v[228:231], v[112:115], v[32:47]
	v_exp_f32_e32 v96, v96
	v_exp_f32_e32 v97, v97
	v_exp_f32_e32 v98, v98
	v_exp_f32_e32 v99, v99
	v_cvt_pk_bf16_f32 v96, v96, v97
	v_cvt_pk_bf16_f32 v97, v98, v99
	v_mfma_f32_16x16x32_bf16 v[164:167], v[172:175], v[112:115], v[164:167]
	v_mfma_f32_32x32x16_bf16 v[80:95], v[212:215], v[152:155], v[80:95]
	v_exp_f32_e32 v100, v100
	v_exp_f32_e32 v101, v101
	v_exp_f32_e32 v102, v102
	v_exp_f32_e32 v103, v103
	v_cvt_pk_bf16_f32 v98, v100, v101
	v_cvt_pk_bf16_f32 v99, v102, v103
	v_mfma_f32_32x32x16_bf16 v[80:95], v[216:219], v[156:159], v[80:95]
	s_waitcnt lgkmcnt(2)
	v_mfma_f32_32x32x16_bf16 v[48:63], v[192:195], v[116:119], v[48:63]
	v_exp_f32_e32 v104, v104
	v_exp_f32_e32 v105, v105
	v_exp_f32_e32 v106, v106
	v_exp_f32_e32 v107, v107
	v_cvt_pk_bf16_f32 v100, v104, v105
	v_cvt_pk_bf16_f32 v101, v106, v107
	v_mfma_f32_32x32x16_bf16 v[32:47], v[196:199], v[116:119], v[32:47]
	v_mfma_f32_16x16x32_bf16 v[164:167], v[172:175], v[116:119], v[164:167]
	v_exp_f32_e32 v108, v108
	v_exp_f32_e32 v109, v109
	v_exp_f32_e32 v110, v110
	v_exp_f32_e32 v111, v111
	v_cvt_pk_bf16_f32 v102, v108, v109
	v_cvt_pk_bf16_f32 v103, v110, v111
	v_mfma_f32_32x32x16_bf16 v[80:95], v[220:223], v[160:163], v[80:95]
	ds_read_b128 v[208:211], v191 offset:24576
	ds_read_b128 v[212:215], v191 offset:28672
	v_mfma_f32_32x32x16_bf16 v[16:31], v[224:227], v[96:99], v[16:31]
	v_exp_f32_e32 v64, v64
	v_exp_f32_e32 v65, v65
	v_exp_f32_e32 v66, v66
	v_exp_f32_e32 v67, v67
	v_cvt_pk_bf16_f32 v64, v64, v65
	v_cvt_pk_bf16_f32 v65, v66, v67
	v_mfma_f32_32x32x16_bf16 v[0:15], v[228:231], v[96:99], v[0:15]
	v_mfma_f32_16x16x32_bf16 v[168:171], v[172:175], v[96:99], v[168:171]
	v_exp_f32_e32 v68, v68
	v_exp_f32_e32 v69, v69
	v_exp_f32_e32 v70, v70
	v_exp_f32_e32 v71, v71
	v_cvt_pk_bf16_f32 v66, v68, v69
	v_cvt_pk_bf16_f32 v67, v70, v71
	v_mfma_f32_32x32x16_bf16 v[16:31], v[192:195], v[100:103], v[16:31]
	v_mfma_f32_32x32x16_bf16 v[0:15], v[196:199], v[100:103], v[0:15]
	v_exp_f32_e32 v72, v72
	v_exp_f32_e32 v73, v73
	v_exp_f32_e32 v74, v74
	v_exp_f32_e32 v75, v75
	v_cvt_pk_bf16_f32 v68, v72, v73
	v_cvt_pk_bf16_f32 v69, v74, v75
	v_mfma_f32_16x16x32_bf16 v[168:171], v[172:175], v[100:103], v[168:171]
	s_waitcnt lgkmcnt(2)
	v_mfma_f32_32x32x16_bf16 v[48:63], v[200:203], v[64:67], v[48:63]
	v_exp_f32_e32 v76, v76
	v_exp_f32_e32 v77, v77
	v_exp_f32_e32 v78, v78
	v_exp_f32_e32 v79, v79
	v_cvt_pk_bf16_f32 v70, v76, v77
	v_cvt_pk_bf16_f32 v71, v78, v79
	v_mfma_f32_32x32x16_bf16 v[32:47], v[204:207], v[64:67], v[32:47]
	v_mfma_f32_16x16x32_bf16 v[164:167], v[172:175], v[64:67], v[164:167]
	v_exp_f32_e32 v80, v80
	v_exp_f32_e32 v81, v81
	v_exp_f32_e32 v82, v82
	v_exp_f32_e32 v83, v83
	v_cvt_pk_bf16_f32 v80, v80, v81
	v_cvt_pk_bf16_f32 v81, v82, v83
	s_waitcnt lgkmcnt(0)
	v_mfma_f32_32x32x16_bf16 v[48:63], v[208:211], v[68:71], v[48:63]
	v_exp_f32_e32 v84, v84
	v_exp_f32_e32 v85, v85
	v_exp_f32_e32 v86, v86
	v_exp_f32_e32 v87, v87
	v_cvt_pk_bf16_f32 v82, v84, v85
	v_cvt_pk_bf16_f32 v83, v86, v87
	v_mfma_f32_32x32x16_bf16 v[32:47], v[212:215], v[68:71], v[32:47]
	v_mfma_f32_16x16x32_bf16 v[164:167], v[172:175], v[68:71], v[164:167]
	v_exp_f32_e32 v88, v88
	v_exp_f32_e32 v89, v89
	v_exp_f32_e32 v90, v90
	v_exp_f32_e32 v91, v91
	v_cvt_pk_bf16_f32 v84, v88, v89
	v_cvt_pk_bf16_f32 v85, v90, v91
	v_mfma_f32_32x32x16_bf16 v[16:31], v[200:203], v[80:83], v[16:31]
	v_exp_f32_e32 v92, v92
	v_exp_f32_e32 v93, v93
	v_exp_f32_e32 v94, v94
	v_exp_f32_e32 v95, v95
	v_cvt_pk_bf16_f32 v86, v92, v93
	v_cvt_pk_bf16_f32 v87, v94, v95
	v_mfma_f32_32x32x16_bf16 v[0:15], v[204:207], v[80:83], v[0:15]
	v_mfma_f32_16x16x32_bf16 v[168:171], v[172:175], v[80:83], v[168:171]
	v_mfma_f32_32x32x16_bf16 v[16:31], v[208:211], v[84:87], v[16:31]
	v_mfma_f32_32x32x16_bf16 v[0:15], v[212:215], v[84:87], v[0:15]
	v_mfma_f32_16x16x32_bf16 v[168:171], v[172:175], v[84:87], v[168:171]
	s_cmp_eq_u32 s28, s25
	s_cbranch_scc1 .LBB0_643
	s_mov_b32 s29, s28
	s_branch .LBB0_637

; #define MFMA32(a, b, c) __builtin_amdgcn_mfma_f32_32x32x16_bf16((a), (b), (c), 0, 0, 0)
; DI float fadd1(float a, float b) { float r; asm("v_add_f32 %0, %1, %2" : "=v"(r) : "v"(a), "v"(b)); return r; }
; template <int NKS>
; DI void attn_tile(const Params& p, int layer, int seq, int slot, int qt, char* smem, bool wr = true) {
;     ...
;     for (int kt = 0; kt < nkt; ++kt) {
;       asm volatile("s_waitcnt vmcnt(0)" ::: "memory");
;       __syncthreads();
;       if (kt + 1 < nkt) stage(kt + 1);
; #pragma unroll 1
;       for (int kh = 0; kh < 2; ++kh) {
;       const u16* sK = (const u16*)(smem + (kt & 1) * 32768 + kh * 8192);
;       const u16* sV = (const u16*)(smem + (kt & 1) * 32768 + 16384 + kh * 8192);
;       auto kb_body = [&](int kb) {
;         bf16x8 kf[NKS];
; #pragma unroll
;         for (int ks = 0; ks < NKS; ++ks) kf[ks] = *(const bf16x8*)(sK + swz(32 * kb + r, 2 * (ks0 + ks) + h));
;         bf16x8 pk[2][2];
; #pragma unroll
;         for (int qb = 0; qb < 2; ++qb) {
;           f32x16 st;
; #pragma unroll
;           for (int i = 0; i < 16; ++i) st[i] = SUB ? ncb[qb] : 0.f;
; #pragma unroll
;           for (int ks = 0; ks < NKS; ++ks) st = MFMA32(kf[ks], qf[qb][ks], st);
;           if constexpr (SUB) {
;             float ls = 0.f;
; #pragma unroll
;             for (int i = 0; i < 16; ++i) { float e = __builtin_amdgcn_exp2f(st[i]); st[i] = e; ls = fadd1(ls, e); }
;             lsum[qb] += ls;
;             pk[qb][0] = pack8(st, 0); pk[qb][1] = pack8(st, 1);
;           } else {
; #pragma unroll
;             for (int i = 0; i < 16; ++i) st[i] = __builtin_amdgcn_exp2f(st[i]);
;             pk[qb][0] = pack8(st, 0); pk[qb][1] = pack8(st, 1);
;             ls4[qb] = __builtin_amdgcn_mfma_f32_16x16x32_bf16(selA, pk[qb][0], ls4[qb], 0, 0, 0);
;             ls4[qb] = __builtin_amdgcn_mfma_f32_16x16x32_bf16(selA, pk[qb][1], ls4[qb], 0, 0, 0);
;           }
;         }
; #pragma unroll
;         for (int eb = 0; eb < 2; ++eb)
; #pragma unroll
;           for (int s2 = 0; s2 < 2; ++s2) {
;             bf16x8 vf = *(const bf16x8*)(sV + swz(32 * eb + r, 4 * kb + 2 * s2 + h));
; #pragma unroll
;             for (int qb = 0; qb < 2; ++qb) O[qb][eb] = MFMA32(vf, pk[qb][s2], O[qb][eb]);
;           }
;       };
.LBB0_671:
	s_waitcnt vmcnt(0)
	s_lshl_b32 s4, s37, 15
	s_and_b32 s4, s4, 0x8000
	v_add3_u32 v128, s4, v172, v178
	v_add3_u32 v130, s4, v173, v178
	v_add3_u32 v131, s4, v174, v178
	v_add3_u32 v188, s4, v175, v178
	v_add3_u32 v189, s4, v176, v178
	v_add3_u32 v190, s4, v177, v178
	s_add_i32 s36, s37, 1
	s_cmp_ge_u32 s36, s31
	s_waitcnt vmcnt(0)
	s_barrier
	ds_read_b128 v[180:183], v128
	ds_read_b128 v[184:187], v130
	ds_read_b128 v[204:207], v128 offset:4096
	ds_read_b128 v[208:211], v130 offset:4096
	ds_read_b128 v[212:215], v131 offset:16384
	ds_read_b128 v[216:219], v131 offset:20480
	ds_read_b128 v[220:223], v188 offset:16384
	ds_read_b128 v[224:227], v188 offset:20480
	ds_read_b128 v[228:231], v189 offset:16384
	s_cbranch_scc1 .LBB0_673
	s_lshl_b32 s4, s36, 15
	s_and_b32 s4, s4, 0x8000
	s_lshl_b32 s14, s36, 8
	s_add_i32 s4, s34, s4
	s_add_i32 s38, s14, s35
	s_add_i32 s5, s4, 0x4000
	s_lshl_b32 s39, s38, 8
	s_mov_b32 m0, s4
	s_mov_b32 s14, s10
	buffer_load_dwordx4 v170, s[8:11], s39 offen lds
	s_mov_b32 s15, s11
	s_mov_b32 m0, s5
	s_or_b32 s5, s39, 0x4000
	buffer_load_dwordx4 v171, s[12:15], s38 offen lds
	s_add_i32 m0, s4, 0x1000
	s_nop 0
	buffer_load_dwordx4 v170, s[8:11], s5 offen lds
	s_add_i32 m0, s4, 0x5000
	s_add_i32 s5, s38, 0x300000
	buffer_load_dwordx4 v171, s[12:15], s5 offen lds
	s_or_b32 s5, s38, 0x80
	s_add_i32 m0, s4, 0x2000
	s_lshl_b32 s40, s5, 8
	buffer_load_dwordx4 v170, s[8:11], s40 offen lds
	s_add_i32 m0, s4, 0x6000
	s_add_i32 s38, s38, 0x300080
	buffer_load_dwordx4 v171, s[12:15], s5 offen lds
	s_add_i32 m0, s4, 0x3000
	s_or_b32 s5, s39, 0xc000
	buffer_load_dwordx4 v170, s[8:11], s5 offen lds
	s_add_i32 m0, s4, 0x7000
	s_nop 0
	buffer_load_dwordx4 v171, s[12:15], s38 offen lds
.LBB0_673:
.LBB0_674:
	s_waitcnt lgkmcnt(7)
	v_mfma_f32_32x32x16_bf16 v[112:127], v[180:183], v[132:135], 0
	v_mfma_f32_32x32x16_bf16 v[112:127], v[184:187], v[136:139], v[112:127]
	v_mfma_f32_32x32x16_bf16 v[96:111], v[180:183], v[140:143], 0
	v_mfma_f32_32x32x16_bf16 v[96:111], v[184:187], v[144:147], v[96:111]
	ds_read_b128 v[180:183], v189 offset:20480
	ds_read_b128 v[184:187], v190 offset:16384
	s_waitcnt lgkmcnt(7)
	v_mfma_f32_32x32x16_bf16 v[64:79], v[204:207], v[132:135], 0
	v_mfma_f32_32x32x16_bf16 v[64:79], v[208:211], v[136:139], v[64:79]
	s_nop 4
	v_exp_f32_e32 v112, v112
	v_exp_f32_e32 v113, v113
	v_exp_f32_e32 v114, v114
	v_exp_f32_e32 v115, v115
	v_cvt_pk_bf16_f32 v112, v112, v113
	v_cvt_pk_bf16_f32 v113, v114, v115
	v_mfma_f32_32x32x16_bf16 v[80:95], v[204:207], v[140:143], 0
	ds_read_b128 v[204:207], v190 offset:20480
	v_exp_f32_e32 v116, v116
	v_exp_f32_e32 v117, v117
	v_exp_f32_e32 v118, v118
	v_exp_f32_e32 v119, v119
	v_cvt_pk_bf16_f32 v114, v116, v117
	v_cvt_pk_bf16_f32 v115, v118, v119
	v_mfma_f32_32x32x16_bf16 v[80:95], v[208:211], v[144:147], v[80:95]
	v_exp_f32_e32 v120, v120
	v_exp_f32_e32 v121, v121
	v_exp_f32_e32 v122, v122
	v_exp_f32_e32 v123, v123
	v_cvt_pk_bf16_f32 v116, v120, v121
	v_cvt_pk_bf16_f32 v117, v122, v123
	s_waitcnt lgkmcnt(6)
	v_mfma_f32_32x32x16_bf16 v[48:63], v[212:215], v[112:115], v[48:63]
	v_exp_f32_e32 v124, v124
	v_exp_f32_e32 v125, v125
	v_exp_f32_e32 v126, v126
	v_exp_f32_e32 v127, v127
	v_cvt_pk_bf16_f32 v118, v124, v125
	v_cvt_pk_bf16_f32 v119, v126, v127
	v_mfma_f32_32x32x16_bf16 v[32:47], v[216:219], v[112:115], v[32:47]
	v_exp_f32_e32 v96, v96
	v_exp_f32_e32 v97, v97
	v_exp_f32_e32 v98, v98
	v_exp_f32_e32 v99, v99
	v_cvt_pk_bf16_f32 v96, v96, v97
	v_cvt_pk_bf16_f32 v97, v98, v99
	v_mfma_f32_16x16x32_bf16 v[148:151], v[156:159], v[112:115], v[148:151]
	s_waitcnt lgkmcnt(4)
	v_mfma_f32_32x32x16_bf16 v[48:63], v[220:223], v[116:119], v[48:63]
	v_exp_f32_e32 v100, v100
	v_exp_f32_e32 v101, v101
	v_exp_f32_e32 v102, v102
	v_exp_f32_e32 v103, v103
	v_cvt_pk_bf16_f32 v98, v100, v101
	v_cvt_pk_bf16_f32 v99, v102, v103
	v_mfma_f32_32x32x16_bf16 v[32:47], v[224:227], v[116:119], v[32:47]
	v_mfma_f32_16x16x32_bf16 v[148:151], v[156:159], v[116:119], v[148:151]
	v_exp_f32_e32 v104, v104
	v_exp_f32_e32 v105, v105
	v_exp_f32_e32 v106, v106
	v_exp_f32_e32 v107, v107
	v_cvt_pk_bf16_f32 v100, v104, v105
	v_cvt_pk_bf16_f32 v101, v106, v107
	v_mfma_f32_32x32x16_bf16 v[16:31], v[212:215], v[96:99], v[16:31]
	v_exp_f32_e32 v108, v108
	v_exp_f32_e32 v109, v109
	v_exp_f32_e32 v110, v110
	v_exp_f32_e32 v111, v111
	v_cvt_pk_bf16_f32 v102, v108, v109
	v_cvt_pk_bf16_f32 v103, v110, v111
	v_mfma_f32_32x32x16_bf16 v[0:15], v[216:219], v[96:99], v[0:15]
	v_mfma_f32_16x16x32_bf16 v[152:155], v[156:159], v[96:99], v[152:155]
	v_exp_f32_e32 v64, v64
	v_exp_f32_e32 v65, v65
	v_exp_f32_e32 v66, v66
	v_exp_f32_e32 v67, v67
	v_cvt_pk_bf16_f32 v64, v64, v65
	v_cvt_pk_bf16_f32 v65, v66, v67
	v_mfma_f32_32x32x16_bf16 v[16:31], v[220:223], v[100:103], v[16:31]
	v_mfma_f32_32x32x16_bf16 v[0:15], v[224:227], v[100:103], v[0:15]
	v_exp_f32_e32 v68, v68
	v_exp_f32_e32 v69, v69
	v_exp_f32_e32 v70, v70
	v_exp_f32_e32 v71, v71
	v_cvt_pk_bf16_f32 v66, v68, v69
	v_cvt_pk_bf16_f32 v67, v70, v71
	v_mfma_f32_16x16x32_bf16 v[152:155], v[156:159], v[100:103], v[152:155]
	s_waitcnt lgkmcnt(2)
	v_mfma_f32_32x32x16_bf16 v[48:63], v[228:231], v[64:67], v[48:63]
	v_exp_f32_e32 v72, v72
	v_exp_f32_e32 v73, v73
	v_exp_f32_e32 v74, v74
	v_exp_f32_e32 v75, v75
	v_cvt_pk_bf16_f32 v68, v72, v73
	v_cvt_pk_bf16_f32 v69, v74, v75
	v_mfma_f32_32x32x16_bf16 v[32:47], v[180:183], v[64:67], v[32:47]
	v_mfma_f32_16x16x32_bf16 v[148:151], v[156:159], v[64:67], v[148:151]
	v_exp_f32_e32 v76, v76
	v_exp_f32_e32 v77, v77
	v_exp_f32_e32 v78, v78
	v_exp_f32_e32 v79, v79
	v_cvt_pk_bf16_f32 v70, v76, v77
	v_cvt_pk_bf16_f32 v71, v78, v79
	s_waitcnt lgkmcnt(0)
; #define MFMA32(a, b, c) __builtin_amdgcn_mfma_f32_32x32x16_bf16((a), (b), (c), 0, 0, 0)
; DI float fadd1(float a, float b) { float r; asm("v_add_f32 %0, %1, %2" : "=v"(r) : "v"(a), "v"(b)); return r; }
; template <int NKS>
; DI void attn_tile(const Params& p, int layer, int seq, int slot, int qt, char* smem, bool wr = true) {
;     ...
;       auto kb_body = [&](int kb) {
;         bf16x8 kf[NKS];
; #pragma unroll
;         for (int ks = 0; ks < NKS; ++ks) kf[ks] = *(const bf16x8*)(sK + swz(32 * kb + r, 2 * (ks0 + ks) + h));
;         bf16x8 pk[2][2];
; #pragma unroll
;         for (int qb = 0; qb < 2; ++qb) {
;           f32x16 st;
; #pragma unroll
;           for (int i = 0; i < 16; ++i) st[i] = SUB ? ncb[qb] : 0.f;
; #pragma unroll
;           for (int ks = 0; ks < NKS; ++ks) st = MFMA32(kf[ks], qf[qb][ks], st);
;           if constexpr (SUB) {
;             float ls = 0.f;
; #pragma unroll
;             for (int i = 0; i < 16; ++i) { float e = __builtin_amdgcn_exp2f(st[i]); st[i] = e; ls = fadd1(ls, e); }
;             lsum[qb] += ls;
;             pk[qb][0] = pack8(st, 0); pk[qb][1] = pack8(st, 1);
;           } else {
; #pragma unroll
;             for (int i = 0; i < 16; ++i) st[i] = __builtin_amdgcn_exp2f(st[i]);
;             pk[qb][0] = pack8(st, 0); pk[qb][1] = pack8(st, 1);
;             ls4[qb] = __builtin_amdgcn_mfma_f32_16x16x32_bf16(selA, pk[qb][0], ls4[qb], 0, 0, 0);
;             ls4[qb] = __builtin_amdgcn_mfma_f32_16x16x32_bf16(selA, pk[qb][1], ls4[qb], 0, 0, 0);
;           }
;         }
; #pragma unroll
;         for (int eb = 0; eb < 2; ++eb)
; #pragma unroll
;           for (int s2 = 0; s2 < 2; ++s2) {
;             bf16x8 vf = *(const bf16x8*)(sV + swz(32 * eb + r, 4 * kb + 2 * s2 + h));
; #pragma unroll
;             for (int qb = 0; qb < 2; ++qb) O[qb][eb] = MFMA32(vf, pk[qb][s2], O[qb][eb]);
;           }
;       };
;       if constexpr (SUB) {
; #pragma unroll 1
;         for (int kb = 0; kb < 2; ++kb) kb_body(kb);
;       } else {
;         kb_body(0); kb_body(1);
;       }
;       }
;     }
	s_nop 0
	v_mfma_f32_32x32x16_bf16 v[48:63], v[184:187], v[68:71], v[48:63]
	v_exp_f32_e32 v80, v80
	v_exp_f32_e32 v81, v81
	v_exp_f32_e32 v82, v82
	v_exp_f32_e32 v83, v83
	v_cvt_pk_bf16_f32 v80, v80, v81
	v_cvt_pk_bf16_f32 v81, v82, v83
	v_mfma_f32_32x32x16_bf16 v[32:47], v[204:207], v[68:71], v[32:47]
	v_mfma_f32_16x16x32_bf16 v[148:151], v[156:159], v[68:71], v[148:151]
	v_exp_f32_e32 v84, v84
	v_exp_f32_e32 v85, v85
	v_exp_f32_e32 v86, v86
	v_exp_f32_e32 v87, v87
	v_cvt_pk_bf16_f32 v82, v84, v85
	v_cvt_pk_bf16_f32 v83, v86, v87
	v_exp_f32_e32 v88, v88
	v_exp_f32_e32 v89, v89
	v_exp_f32_e32 v90, v90
	v_exp_f32_e32 v91, v91
	v_cvt_pk_bf16_f32 v84, v88, v89
	v_cvt_pk_bf16_f32 v85, v90, v91
	v_mfma_f32_32x32x16_bf16 v[16:31], v[228:231], v[80:83], v[16:31]
	v_exp_f32_e32 v92, v92
	v_exp_f32_e32 v93, v93
	v_exp_f32_e32 v94, v94
	v_exp_f32_e32 v95, v95
	v_cvt_pk_bf16_f32 v86, v92, v93
	v_cvt_pk_bf16_f32 v87, v94, v95
	v_mfma_f32_32x32x16_bf16 v[0:15], v[180:183], v[80:83], v[0:15]
	v_mfma_f32_16x16x32_bf16 v[152:155], v[156:159], v[80:83], v[152:155]
	v_mfma_f32_32x32x16_bf16 v[16:31], v[184:187], v[84:87], v[16:31]
	v_mfma_f32_32x32x16_bf16 v[0:15], v[204:207], v[84:87], v[0:15]
	v_mfma_f32_16x16x32_bf16 v[152:155], v[156:159], v[84:87], v[152:155]
	ds_read_b128 v[180:183], v128 offset:8192
	ds_read_b128 v[184:187], v130 offset:8192
	ds_read_b128 v[204:207], v128 offset:12288
	ds_read_b128 v[208:211], v130 offset:12288
	ds_read_b128 v[212:215], v131 offset:24576
	ds_read_b128 v[216:219], v131 offset:28672
	ds_read_b128 v[220:223], v188 offset:24576
	ds_read_b128 v[224:227], v188 offset:28672
	ds_read_b128 v[228:231], v189 offset:24576
	s_waitcnt lgkmcnt(7)
	v_mfma_f32_32x32x16_bf16 v[112:127], v[180:183], v[132:135], 0
	v_mfma_f32_32x32x16_bf16 v[112:127], v[184:187], v[136:139], v[112:127]
	v_mfma_f32_32x32x16_bf16 v[96:111], v[180:183], v[140:143], 0
	v_mfma_f32_32x32x16_bf16 v[96:111], v[184:187], v[144:147], v[96:111]
	ds_read_b128 v[180:183], v189 offset:28672
	ds_read_b128 v[184:187], v190 offset:24576
	s_waitcnt lgkmcnt(7)
	v_mfma_f32_32x32x16_bf16 v[64:79], v[204:207], v[132:135], 0
	v_mfma_f32_32x32x16_bf16 v[64:79], v[208:211], v[136:139], v[64:79]
	s_nop 4
	v_exp_f32_e32 v112, v112
	v_exp_f32_e32 v113, v113
	v_exp_f32_e32 v114, v114
	v_exp_f32_e32 v115, v115
	v_cvt_pk_bf16_f32 v112, v112, v113
	v_cvt_pk_bf16_f32 v113, v114, v115
	v_mfma_f32_32x32x16_bf16 v[80:95], v[204:207], v[140:143], 0
	ds_read_b128 v[204:207], v190 offset:28672
	v_exp_f32_e32 v116, v116
	v_exp_f32_e32 v117, v117
	v_exp_f32_e32 v118, v118
	v_exp_f32_e32 v119, v119
	v_cvt_pk_bf16_f32 v114, v116, v117
	v_cvt_pk_bf16_f32 v115, v118, v119
	v_mfma_f32_32x32x16_bf16 v[80:95], v[208:211], v[144:147], v[80:95]
	v_exp_f32_e32 v120, v120
	v_exp_f32_e32 v121, v121
	v_exp_f32_e32 v122, v122
	v_exp_f32_e32 v123, v123
	v_cvt_pk_bf16_f32 v116, v120, v121
	v_cvt_pk_bf16_f32 v117, v122, v123
	s_waitcnt lgkmcnt(6)
	v_mfma_f32_32x32x16_bf16 v[48:63], v[212:215], v[112:115], v[48:63]
	v_exp_f32_e32 v124, v124
	v_exp_f32_e32 v125, v125
	v_exp_f32_e32 v126, v126
	v_exp_f32_e32 v127, v127
	v_cvt_pk_bf16_f32 v118, v124, v125
	v_cvt_pk_bf16_f32 v119, v126, v127
	v_mfma_f32_32x32x16_bf16 v[32:47], v[216:219], v[112:115], v[32:47]
	v_exp_f32_e32 v96, v96
	v_exp_f32_e32 v97, v97
	v_exp_f32_e32 v98, v98
	v_exp_f32_e32 v99, v99
	v_cvt_pk_bf16_f32 v96, v96, v97
	v_cvt_pk_bf16_f32 v97, v98, v99
	v_mfma_f32_16x16x32_bf16 v[148:151], v[156:159], v[112:115], v[148:151]
	s_waitcnt lgkmcnt(4)
	v_mfma_f32_32x32x16_bf16 v[48:63], v[220:223], v[116:119], v[48:63]
	v_exp_f32_e32 v100, v100
	v_exp_f32_e32 v101, v101
	v_exp_f32_e32 v102, v102
	v_exp_f32_e32 v103, v103
	v_cvt_pk_bf16_f32 v98, v100, v101
	v_cvt_pk_bf16_f32 v99, v102, v103
	v_mfma_f32_32x32x16_bf16 v[32:47], v[224:227], v[116:119], v[32:47]
	v_mfma_f32_16x16x32_bf16 v[148:151], v[156:159], v[116:119], v[148:151]
	v_exp_f32_e32 v104, v104
	v_exp_f32_e32 v105, v105
	v_exp_f32_e32 v106, v106
	v_exp_f32_e32 v107, v107
	v_cvt_pk_bf16_f32 v100, v104, v105
	v_cvt_pk_bf16_f32 v101, v106, v107
	v_mfma_f32_32x32x16_bf16 v[16:31], v[212:215], v[96:99], v[16:31]
	v_exp_f32_e32 v108, v108
	v_exp_f32_e32 v109, v109
	v_exp_f32_e32 v110, v110
	v_exp_f32_e32 v111, v111
	v_cvt_pk_bf16_f32 v102, v108, v109
	v_cvt_pk_bf16_f32 v103, v110, v111
	v_mfma_f32_32x32x16_bf16 v[0:15], v[216:219], v[96:99], v[0:15]
	v_mfma_f32_16x16x32_bf16 v[152:155], v[156:159], v[96:99], v[152:155]
	v_exp_f32_e32 v64, v64
	v_exp_f32_e32 v65, v65
	v_exp_f32_e32 v66, v66
	v_exp_f32_e32 v67, v67
	v_cvt_pk_bf16_f32 v64, v64, v65
	v_cvt_pk_bf16_f32 v65, v66, v67
	v_mfma_f32_32x32x16_bf16 v[16:31], v[220:223], v[100:103], v[16:31]
	v_mfma_f32_32x32x16_bf16 v[0:15], v[224:227], v[100:103], v[0:15]
	v_exp_f32_e32 v68, v68
	v_exp_f32_e32 v69, v69
	v_exp_f32_e32 v70, v70
	v_exp_f32_e32 v71, v71
	v_cvt_pk_bf16_f32 v66, v68, v69
	v_cvt_pk_bf16_f32 v67, v70, v71
	v_mfma_f32_16x16x32_bf16 v[152:155], v[156:159], v[100:103], v[152:155]
	s_waitcnt lgkmcnt(2)
	v_mfma_f32_32x32x16_bf16 v[48:63], v[228:231], v[64:67], v[48:63]
	v_exp_f32_e32 v72, v72
	v_exp_f32_e32 v73, v73
	v_exp_f32_e32 v74, v74
	v_exp_f32_e32 v75, v75
	v_cvt_pk_bf16_f32 v68, v72, v73
	v_cvt_pk_bf16_f32 v69, v74, v75
	v_mfma_f32_32x32x16_bf16 v[32:47], v[180:183], v[64:67], v[32:47]
	v_mfma_f32_16x16x32_bf16 v[148:151], v[156:159], v[64:67], v[148:151]
	v_exp_f32_e32 v76, v76
	v_exp_f32_e32 v77, v77
	v_exp_f32_e32 v78, v78
	v_exp_f32_e32 v79, v79
	v_cvt_pk_bf16_f32 v70, v76, v77
	v_cvt_pk_bf16_f32 v71, v78, v79
	s_waitcnt lgkmcnt(0)
	s_nop 0
	v_mfma_f32_32x32x16_bf16 v[48:63], v[184:187], v[68:71], v[48:63]
	v_exp_f32_e32 v80, v80
	v_exp_f32_e32 v81, v81
	v_exp_f32_e32 v82, v82
	v_exp_f32_e32 v83, v83
	v_cvt_pk_bf16_f32 v80, v80, v81
	v_cvt_pk_bf16_f32 v81, v82, v83
	v_mfma_f32_32x32x16_bf16 v[32:47], v[204:207], v[68:71], v[32:47]
	v_mfma_f32_16x16x32_bf16 v[148:151], v[156:159], v[68:71], v[148:151]
	v_exp_f32_e32 v84, v84
	v_exp_f32_e32 v85, v85
	v_exp_f32_e32 v86, v86
	v_exp_f32_e32 v87, v87
	v_cvt_pk_bf16_f32 v82, v84, v85
	v_cvt_pk_bf16_f32 v83, v86, v87
	v_exp_f32_e32 v88, v88
	v_exp_f32_e32 v89, v89
	v_exp_f32_e32 v90, v90
	v_exp_f32_e32 v91, v91
	v_cvt_pk_bf16_f32 v84, v88, v89
	v_cvt_pk_bf16_f32 v85, v90, v91
	v_mfma_f32_32x32x16_bf16 v[16:31], v[228:231], v[80:83], v[16:31]
	v_exp_f32_e32 v92, v92
	v_exp_f32_e32 v93, v93
	v_exp_f32_e32 v94, v94
	v_exp_f32_e32 v95, v95
	v_cvt_pk_bf16_f32 v86, v92, v93
	v_cvt_pk_bf16_f32 v87, v94, v95
	v_mfma_f32_32x32x16_bf16 v[0:15], v[180:183], v[80:83], v[0:15]
	v_mfma_f32_16x16x32_bf16 v[152:155], v[156:159], v[80:83], v[152:155]
	v_mfma_f32_32x32x16_bf16 v[16:31], v[184:187], v[84:87], v[16:31]
	v_mfma_f32_32x32x16_bf16 v[0:15], v[204:207], v[84:87], v[0:15]
	v_mfma_f32_16x16x32_bf16 v[152:155], v[156:159], v[84:87], v[152:155]
	s_cmp_eq_u32 s36, s31
	s_cbranch_scc1 .LBB0_677
	s_mov_b32 s37, s36
	s_branch .LBB0_671

; template <int NKS>
; DI void attn_tile(const Params& p, int layer, int seq, int slot, int qt, char* smem, bool wr = true) {
;     ...
;     for (int kt = 0; kt < nkt; ++kt) {
;       asm volatile("s_waitcnt vmcnt(0)" ::: "memory");
;       __syncthreads();
;       if (kt + 1 < nkt) stage(kt + 1);
; #pragma unroll 1
;       for (int kh = 0; kh < 2; ++kh) {
;       const u16* sK = (const u16*)(smem + (kt & 1) * 32768 + kh * 8192);
;       const u16* sV = (const u16*)(smem + (kt & 1) * 32768 + 16384 + kh * 8192);
;       auto kb_body = [&](int kb) {
;         bf16x8 kf[NKS];
; #pragma unroll
;         for (int ks = 0; ks < NKS; ++ks) kf[ks] = *(const bf16x8*)(sK + swz(32 * kb + r, 2 * (ks0 + ks) + h));
.LBB0_1414:
	s_waitcnt vmcnt(0)
	s_lshl_b32 s4, s37, 15
	s_and_b32 s4, s4, 0x8000
	v_add3_u32 v128, s4, v173, v179
	v_add3_u32 v130, s4, v174, v179
	v_add3_u32 v131, s4, v175, v179
	v_add3_u32 v188, s4, v176, v179
	v_add3_u32 v189, s4, v177, v179
	v_add3_u32 v190, s4, v178, v179
	s_add_i32 s36, s37, 1
	s_cmp_ge_u32 s36, s31
	s_waitcnt vmcnt(0)
	s_barrier
	ds_read_b128 v[180:183], v128
	ds_read_b128 v[184:187], v130
	ds_read_b128 v[204:207], v128 offset:4096
	ds_read_b128 v[208:211], v130 offset:4096
	ds_read_b128 v[212:215], v131 offset:16384
	ds_read_b128 v[216:219], v131 offset:20480
	ds_read_b128 v[220:223], v188 offset:16384
	ds_read_b128 v[224:227], v188 offset:20480
	ds_read_b128 v[228:231], v189 offset:16384
	s_cbranch_scc1 .LBB0_1416
	s_lshl_b32 s4, s36, 15
	s_and_b32 s4, s4, 0x8000
	s_lshl_b32 s14, s36, 8
	s_add_i32 s4, s34, s4
	s_add_i32 s38, s14, s35
	s_add_i32 s5, s4, 0x4000
	s_lshl_b32 s39, s38, 8
	s_mov_b32 m0, s4
	s_mov_b32 s14, s10
	buffer_load_dwordx4 v171, s[8:11], s39 offen lds
	s_mov_b32 s15, s11
	s_mov_b32 m0, s5
	s_or_b32 s5, s39, 0x4000
	buffer_load_dwordx4 v172, s[12:15], s38 offen lds
	s_add_i32 m0, s4, 0x1000
	s_nop 0
	buffer_load_dwordx4 v171, s[8:11], s5 offen lds
	s_add_i32 m0, s4, 0x5000
	s_add_i32 s5, s38, 0x300000
	buffer_load_dwordx4 v172, s[12:15], s5 offen lds
	s_or_b32 s5, s38, 0x80
	s_add_i32 m0, s4, 0x2000
	s_lshl_b32 s40, s5, 8
	buffer_load_dwordx4 v171, s[8:11], s40 offen lds
	s_add_i32 m0, s4, 0x6000
	s_add_i32 s38, s38, 0x300080
	buffer_load_dwordx4 v172, s[12:15], s5 offen lds
	s_add_i32 m0, s4, 0x3000
	s_or_b32 s5, s39, 0xc000
	buffer_load_dwordx4 v171, s[8:11], s5 offen lds
	s_add_i32 m0, s4, 0x7000
	s_nop 0
	buffer_load_dwordx4 v172, s[12:15], s38 offen lds
